# loop-edge edit: attention loop counter and pointer copies moved ahead of the wait+barrier at the loop head
# speedup vs baseline: 1.0019x; 1.0019x over previous
; #define LAS __attribute__((address_space(3)))
; #define ATT_DMA2(ss) do { _Pragma("unroll") for (int hf = 0; hf < 2; ++hf) _Pragma("unroll") for (int j = 0; j < 4; ++j) if ((j * 8 + wave) * 64 < NKCH + NVCH) { \
;         __builtin_amdgcn_global_load_lds((const unsigned*)src[j], (LAS unsigned*)(lds + ((ss) * 2 + hf) * TILE + (j * 8 + wave) * 1024), 16, 0, 0); src[j] += step[j]; } } while (0)
; template <int DQK, int DV, int kpitch, int vpitch>
; DI void attn_map(LAS unsigned char* lds, const bf16x8 (&qf)[DQK / 16], const bf16* Kg, const bf16* Vg, f32x16 (&o)[DV / 32], float& lsum, int tid, int lane) {
;     ...
;     for (int s = 0; s < NSTEP; ++s) {
;         asm volatile("s_waitcnt vmcnt(0)" ::: "memory");
;         __builtin_amdgcn_s_barrier();
;         asm volatile("" ::: "memory");
;         if (s + 1 < NSTEP) ATT_DMA2((s + 1) & 1);
;         const LAS unsigned char* ta = lds + (s & 1) * 2 * TILE;
.LBB0_1825:
	s_add_i32 s25, s26, 0x10000
	s_waitcnt vmcnt(0)
	s_barrier
	s_branch .LBB0_1824

; #define LAS __attribute__((address_space(3)))
; #define ATT_DMA2(ss) do { _Pragma("unroll") for (int hf = 0; hf < 2; ++hf) _Pragma("unroll") for (int j = 0; j < 4; ++j) if ((j * 8 + wave) * 64 < NKCH + NVCH) { \
;         __builtin_amdgcn_global_load_lds((const unsigned*)src[j], (LAS unsigned*)(lds + ((ss) * 2 + hf) * TILE + (j * 8 + wave) * 1024), 16, 0, 0); src[j] += step[j]; } } while (0)
; template <int DQK, int DV, int kpitch, int vpitch>
; DI void attn_map(LAS unsigned char* lds, const bf16x8 (&qf)[DQK / 16], const bf16* Kg, const bf16* Vg, f32x16 (&o)[DV / 32], float& lsum, int tid, int lane) {
;     ...
;     for (int s = 0; s < NSTEP; ++s) {
;         asm volatile("s_waitcnt vmcnt(0)" ::: "memory");
;         __builtin_amdgcn_s_barrier();
;         asm volatile("" ::: "memory");
;         if (s + 1 < NSTEP) ATT_DMA2((s + 1) & 1);
;         const LAS unsigned char* ta = lds + (s & 1) * 2 * TILE;
;         attn_step2<DQK, DV, KSTR, VSTR>(ta, ta + TILE, koff, voff, qf, o, l0, l1, l2, l3);
.LBB0_1953:
	s_add_i32 s26, s27, 0x10000
	v_mov_b64_e32 v[96:97], v[32:33]
	v_mov_b64_e32 v[98:99], v[34:35]
	v_mov_b64_e32 v[100:101], v[36:37]
	v_mov_b64_e32 v[102:103], v[38:39]
	s_waitcnt vmcnt(0)
	s_barrier
	s_branch .LBB0_1952
